# adds: attention loop head dead-branch removal; GLA chunk step: TOT prefix reads issued together, pass A state-update LDS reads batched with counted lgkmcnt
# speedup vs baseline: 1.0066x; 1.0019x over previous
; template <bool NEEDQ> __device__ __forceinline__ float chunk_front(const ChunkRegs& C, const ChunkRegs& N, bool stage_next, int cur, int dir, const bf16x8& bhi, const bf16x8& blo, float biasd, LAS unsigned char* lds, int tid) {
;     ...
;         TOT[grp * 64 + d] = la[7];
;     } else {
; #pragma unroll
;         for (int i = 6; i >= 0; --i) la[i] += la[i + 1];
;         TOT[grp * 64 + d] = la[0];
;     }
;     __syncthreads();
;     float pre = 0.f, tot = 0.f;
; #pragma unroll
;     for (int g = 0; g < 8; ++g) { const float tv = TOT[g * 64 + d]; tot += tv; if (dir == 0 ? (g < grp) : (g > grp)) pre += tv; }
.LBB0_278:
	ds_write_b32 v101, v47 offset:20480
	s_waitcnt lgkmcnt(0)
	s_barrier
	ds_read_b32 v32, v99 offset:20480
	ds_read_b32 v35, v99 offset:20736
	ds_read_b32 v36, v99 offset:20992
	ds_read_b32 v37, v99 offset:21248
	ds_read_b32 v38, v99 offset:21504
	ds_read_b32 v39, v99 offset:21760
	ds_read_b32 v47, v99 offset:22016
	ds_read_b32 v89, v99 offset:22272
	s_and_b64 vcc, exec, s[60:61]
	s_cbranch_vccz .LBB0_280
	s_and_b64 s[66:67], s[6:7], exec
	s_cbranch_execz .LBB0_281
	s_branch .LBB0_282

; template <bool NEEDQ> __device__ __forceinline__ float chunk_front(const ChunkRegs& C, const ChunkRegs& N, bool stage_next, int cur, int dir, const bf16x8& bhi, const bf16x8& blo, float biasd, LAS unsigned char* lds, int tid) {
;     ...
;     float pre = 0.f, tot = 0.f;
; #pragma unroll
;     for (int g = 0; g < 8; ++g) { const float tv = TOT[g * 64 + d]; tot += tv; if (dir == 0 ? (g < grp) : (g > grp)) pre += tv; }
.LBB0_282:
	s_waitcnt lgkmcnt(0)
	v_add_f32_e32 v34, 0, v32
	v_mov_b32_e32 v32, 0
	s_and_saveexec_b64 s[68:69], s[66:67]
	s_cbranch_execnz .LBB0_285
	s_or_b64 exec, exec, s[68:69]
	s_and_b64 vcc, exec, s[40:41]
	s_cbranch_vccnz .LBB0_286

; template <bool NEEDQ> __device__ __forceinline__ float chunk_front(const ChunkRegs& C, const ChunkRegs& N, bool stage_next, int cur, int dir, const bf16x8& bhi, const bf16x8& blo, float biasd, LAS unsigned char* lds, int tid) {
;     ...
;     float pre = 0.f, tot = 0.f;
; #pragma unroll
;     for (int g = 0; g < 8; ++g) { const float tv = TOT[g * 64 + d]; tot += tv; if (dir == 0 ? (g < grp) : (g > grp)) pre += tv; }
.LBB0_285:
	v_mov_b32_e32 v32, v34
	s_or_b64 exec, exec, s[68:69]
	s_and_b64 vcc, exec, s[40:41]
	s_cbranch_vccz .LBB0_284

; template <bool NEEDQ> __device__ __forceinline__ float chunk_front(const ChunkRegs& C, const ChunkRegs& N, bool stage_next, int cur, int dir, const bf16x8& bhi, const bf16x8& blo, float biasd, LAS unsigned char* lds, int tid) {
;     ...
;     float pre = 0.f, tot = 0.f;
; #pragma unroll
;     for (int g = 0; g < 8; ++g) { const float tv = TOT[g * 64 + d]; tot += tv; if (dir == 0 ? (g < grp) : (g > grp)) pre += tv; }
.LBB0_288:
	s_and_saveexec_b64 s[68:69], s[66:67]
	s_cbranch_execnz .LBB0_291
	s_or_b64 exec, exec, s[68:69]
	s_and_b64 vcc, exec, s[40:41]
	s_cbranch_vccnz .LBB0_292

; template <bool NEEDQ> __device__ __forceinline__ float chunk_front(const ChunkRegs& C, const ChunkRegs& N, bool stage_next, int cur, int dir, const bf16x8& bhi, const bf16x8& blo, float biasd, LAS unsigned char* lds, int tid) {
;     ...
;     float pre = 0.f, tot = 0.f;
; #pragma unroll
;     for (int g = 0; g < 8; ++g) { const float tv = TOT[g * 64 + d]; tot += tv; if (dir == 0 ? (g < grp) : (g > grp)) pre += tv; }
.LBB0_291:
	s_waitcnt lgkmcnt(0)
	v_add_f32_e32 v32, v32, v35
	s_or_b64 exec, exec, s[68:69]
	s_and_b64 vcc, exec, s[40:41]
	s_cbranch_vccz .LBB0_290

; template <bool NEEDQ> __device__ __forceinline__ float chunk_front(const ChunkRegs& C, const ChunkRegs& N, bool stage_next, int cur, int dir, const bf16x8& bhi, const bf16x8& blo, float biasd, LAS unsigned char* lds, int tid) {
;     ...
;     float pre = 0.f, tot = 0.f;
; #pragma unroll
;     for (int g = 0; g < 8; ++g) { const float tv = TOT[g * 64 + d]; tot += tv; if (dir == 0 ? (g < grp) : (g > grp)) pre += tv; }
.LBB0_297:
	s_waitcnt lgkmcnt(0)
	v_add_f32_e32 v32, v32, v36
	s_or_b64 exec, exec, s[68:69]
	s_and_b64 vcc, exec, s[40:41]
	s_cbranch_vccz .LBB0_296

; template <bool NEEDQ> __device__ __forceinline__ float chunk_front(const ChunkRegs& C, const ChunkRegs& N, bool stage_next, int cur, int dir, const bf16x8& bhi, const bf16x8& blo, float biasd, LAS unsigned char* lds, int tid) {
;     ...
;     float pre = 0.f, tot = 0.f;
; #pragma unroll
;     for (int g = 0; g < 8; ++g) { const float tv = TOT[g * 64 + d]; tot += tv; if (dir == 0 ? (g < grp) : (g > grp)) pre += tv; }
.LBB0_303:
	s_waitcnt lgkmcnt(0)
	v_add_f32_e32 v32, v32, v37
	s_or_b64 exec, exec, s[68:69]
	s_and_b64 vcc, exec, s[40:41]
	s_cbranch_vccz .LBB0_302

; template <bool NEEDQ> __device__ __forceinline__ float chunk_front(const ChunkRegs& C, const ChunkRegs& N, bool stage_next, int cur, int dir, const bf16x8& bhi, const bf16x8& blo, float biasd, LAS unsigned char* lds, int tid) {
;     ...
;     float pre = 0.f, tot = 0.f;
; #pragma unroll
;     for (int g = 0; g < 8; ++g) { const float tv = TOT[g * 64 + d]; tot += tv; if (dir == 0 ? (g < grp) : (g > grp)) pre += tv; }
.LBB0_309:
	s_waitcnt lgkmcnt(0)
	v_add_f32_e32 v32, v32, v38
	s_or_b64 exec, exec, s[68:69]
	s_and_b64 vcc, exec, s[40:41]
	s_cbranch_vccz .LBB0_308

; template <bool NEEDQ> __device__ __forceinline__ float chunk_front(const ChunkRegs& C, const ChunkRegs& N, bool stage_next, int cur, int dir, const bf16x8& bhi, const bf16x8& blo, float biasd, LAS unsigned char* lds, int tid) {
;     ...
;     float pre = 0.f, tot = 0.f;
; #pragma unroll
;     for (int g = 0; g < 8; ++g) { const float tv = TOT[g * 64 + d]; tot += tv; if (dir == 0 ? (g < grp) : (g > grp)) pre += tv; }
.LBB0_315:
	s_waitcnt lgkmcnt(0)
	v_add_f32_e32 v32, v32, v39
	s_or_b64 exec, exec, s[68:69]
	s_and_b64 vcc, exec, s[40:41]
	s_cbranch_vccz .LBB0_314

; template <bool NEEDQ> __device__ __forceinline__ float chunk_front(const ChunkRegs& C, const ChunkRegs& N, bool stage_next, int cur, int dir, const bf16x8& bhi, const bf16x8& blo, float biasd, LAS unsigned char* lds, int tid) {
;     ...
;     float pre = 0.f, tot = 0.f;
; #pragma unroll
;     for (int g = 0; g < 8; ++g) { const float tv = TOT[g * 64 + d]; tot += tv; if (dir == 0 ? (g < grp) : (g > grp)) pre += tv; }
.LBB0_321:
	s_waitcnt lgkmcnt(0)
	v_add_f32_e32 v32, v32, v47
	s_or_b64 exec, exec, s[68:69]
	s_and_b64 vcc, exec, s[40:41]
	s_cbranch_vccz .LBB0_320

; #define LAS __attribute__((address_space(3)))
; __device__ __forceinline__ int crow(int r, int hi) { return (r & 3) + 8 * (r >> 2) + 4 * hi; }
; __device__ __forceinline__ s16x4 vtr(LAS unsigned char* p) { return __builtin_bit_cast(s16x4, __builtin_amdgcn_ds_read_tr16_b64_v4i16((LAS v4i16_t*)p)); }
; __device__ __forceinline__ void state_update(f32x16& S, int mb, int nb, int LV, LAS unsigned char* lds, int hh, int q4, int pp4, int g1) {
; #pragma unroll
;     for (int s = 0; s < 4; ++s) {
;         LAS unsigned char* kb = lds + L_KT + (16 * s + 8 * hh + q4) * QSTR + (32 * mb + 16 * g1 + 4 * pp4) * 2;
;         LAS unsigned char* vb = lds + LV + (16 * s + 8 * hh + q4) * VSTR + (32 * nb + 16 * g1 + 4 * pp4) * 2;
;         const s16x4 alo = vtr(kb), ahi = vtr(kb + 4 * QSTR), blo = vtr(vb), bhi = vtr(vb + 4 * VSTR);
;         S = __builtin_amdgcn_mfma_f32_32x32x16_bf16((bf16x8){alo[0], alo[1], alo[2], alo[3], ahi[0], ahi[1], ahi[2], ahi[3]},
;                                                     (bf16x8){blo[0], blo[1], blo[2], blo[3], bhi[0], bhi[1], bhi[2], bhi[3]}, S, 0, 0, 0);
;     }
;     LAS float* BT = (LAS float*)(lds + L_BT);
; #pragma unroll
;     for (int r = 0; r < 16; ++r) S[r] *= BT[32 * mb + crow(r, hh)];
; }
.LBB0_330:
	s_or_b64 exec, exec, s[68:69]
	s_and_b64 s[66:67], s[66:67], exec
	s_cselect_b32 s65, s72, 0x1c600
	s_waitcnt lgkmcnt(0)
	s_barrier
	v_add_f32_e32 v114, v114, v34
	v_add3_u32 v40, v106, s65, v107
	ds_read_b64_tr_b16 v[32:33], v112 offset:32256
	ds_read_b64_tr_b16 v[34:35], v112 offset:32832
	ds_read_b64_tr_b16 v[36:37], v40
	ds_read_b64_tr_b16 v[38:39], v40 offset:1280
	ds_read_b64_tr_b16 v[120:121], v112 offset:34560
	ds_read_b64_tr_b16 v[122:123], v112 offset:35136
	ds_read_b64_tr_b16 v[124:125], v40 offset:5120
	ds_read_b64_tr_b16 v[126:127], v40 offset:6400
	ds_read_b64_tr_b16 v[128:129], v112 offset:36864
	ds_read_b64_tr_b16 v[130:131], v112 offset:37440
	ds_read_b64_tr_b16 v[132:133], v40 offset:10240
	ds_read_b64_tr_b16 v[134:135], v40 offset:11520
	s_add_i32 s74, s74, -1
	s_add_i32 s73, s73, 1
	s_cmp_eq_u32 s74, -1
	s_waitcnt lgkmcnt(8)
	v_mfma_f32_32x32x16_bf16 v[0:15], v[32:35], v[36:39], v[0:15]
	ds_read_b64_tr_b16 v[136:137], v112 offset:39168
	ds_read_b64_tr_b16 v[138:139], v112 offset:39744
	ds_read_b64_tr_b16 v[140:141], v40 offset:15360
	ds_read_b64_tr_b16 v[142:143], v40 offset:16640
	s_waitcnt lgkmcnt(8)
	v_mfma_f32_32x32x16_bf16 v[0:15], v[120:123], v[124:127], v[0:15]
	ds_read_b128 v[144:147], v113 offset:22528
	ds_read_b128 v[148:151], v113 offset:22560
	s_waitcnt lgkmcnt(6)
	v_mfma_f32_32x32x16_bf16 v[0:15], v[128:131], v[132:135], v[0:15]
	ds_read_b128 v[152:155], v113 offset:22592
	ds_read_b128 v[156:159], v113 offset:22624
	s_waitcnt lgkmcnt(4)
	v_mfma_f32_32x32x16_bf16 v[0:15], v[136:139], v[140:143], v[0:15]
	s_waitcnt lgkmcnt(0)
	s_nop 10
	v_pk_mul_f32 v[0:1], v[144:145], v[0:1]
	v_pk_mul_f32 v[2:3], v[2:3], v[146:147]
	v_pk_mul_f32 v[4:5], v[4:5], v[148:149]
	v_pk_mul_f32 v[6:7], v[6:7], v[150:151]
	v_pk_mul_f32 v[8:9], v[8:9], v[152:153]
	v_pk_mul_f32 v[10:11], v[10:11], v[154:155]
	v_pk_mul_f32 v[12:13], v[12:13], v[156:157]
	v_pk_mul_f32 v[14:15], v[14:15], v[158:159]
	s_cbranch_scc1 .LBB0_332
	s_waitcnt vmcnt(0)
	v_mov_b64_e32 v[66:67], v[54:55]
	v_mov_b64_e32 v[64:65], v[52:53]
	s_branch .LBB0_270

; template <bool NEEDQ> __device__ __forceinline__ float chunk_front(const ChunkRegs& C, const ChunkRegs& N, bool stage_next, int cur, int dir, const bf16x8& bhi, const bf16x8& blo, float biasd, LAS unsigned char* lds, int tid) {
;     ...
;         TOT[grp * 64 + d] = la[7];
;     } else {
; #pragma unroll
;         for (int i = 6; i >= 0; --i) la[i] += la[i + 1];
;         TOT[grp * 64 + d] = la[0];
;     }
;     __syncthreads();
;     float pre = 0.f, tot = 0.f;
; #pragma unroll
;     for (int g = 0; g < 8; ++g) { const float tv = TOT[g * 64 + d]; tot += tv; if (dir == 0 ? (g < grp) : (g > grp)) pre += tv; }
.LBB0_338:
	ds_write_b32 v101, v31 offset:20480
	s_waitcnt lgkmcnt(0)
	s_barrier
	ds_read_b32 v16, v99 offset:20480
	ds_read_b32 v19, v99 offset:20736
	ds_read_b32 v20, v99 offset:20992
	ds_read_b32 v21, v99 offset:21248
	ds_read_b32 v22, v99 offset:21504
	ds_read_b32 v23, v99 offset:21760
	ds_read_b32 v31, v99 offset:22016
	ds_read_b32 v32, v99 offset:22272
	s_and_b64 vcc, exec, s[40:41]
	s_cbranch_vccnz .LBB0_340
	s_and_b64 s[60:61], s[6:7], exec
	s_cbranch_execz .LBB0_341
	s_branch .LBB0_342

; template <bool NEEDQ> __device__ __forceinline__ float chunk_front(const ChunkRegs& C, const ChunkRegs& N, bool stage_next, int cur, int dir, const bf16x8& bhi, const bf16x8& blo, float biasd, LAS unsigned char* lds, int tid) {
;     ...
;     float pre = 0.f, tot = 0.f;
; #pragma unroll
;     for (int g = 0; g < 8; ++g) { const float tv = TOT[g * 64 + d]; tot += tv; if (dir == 0 ? (g < grp) : (g > grp)) pre += tv; }
.LBB0_342:
	s_waitcnt lgkmcnt(0)
	v_add_f32_e32 v16, 0, v16
	v_mov_b32_e32 v18, 0
	s_and_saveexec_b64 s[62:63], s[60:61]
	s_cbranch_execnz .LBB0_345
	s_or_b64 exec, exec, s[62:63]
	s_and_b64 vcc, exec, s[40:41]
	s_cbranch_vccnz .LBB0_346

; template <bool NEEDQ> __device__ __forceinline__ float chunk_front(const ChunkRegs& C, const ChunkRegs& N, bool stage_next, int cur, int dir, const bf16x8& bhi, const bf16x8& blo, float biasd, LAS unsigned char* lds, int tid) {
;     ...
;     float pre = 0.f, tot = 0.f;
; #pragma unroll
;     for (int g = 0; g < 8; ++g) { const float tv = TOT[g * 64 + d]; tot += tv; if (dir == 0 ? (g < grp) : (g > grp)) pre += tv; }
.LBB0_345:
	v_mov_b32_e32 v18, v16
	s_or_b64 exec, exec, s[62:63]
	s_and_b64 vcc, exec, s[40:41]
	s_cbranch_vccz .LBB0_344

; template <bool NEEDQ> __device__ __forceinline__ float chunk_front(const ChunkRegs& C, const ChunkRegs& N, bool stage_next, int cur, int dir, const bf16x8& bhi, const bf16x8& blo, float biasd, LAS unsigned char* lds, int tid) {
;     ...
;     float pre = 0.f, tot = 0.f;
; #pragma unroll
;     for (int g = 0; g < 8; ++g) { const float tv = TOT[g * 64 + d]; tot += tv; if (dir == 0 ? (g < grp) : (g > grp)) pre += tv; }
.LBB0_348:
	s_and_saveexec_b64 s[62:63], s[60:61]
	s_cbranch_execnz .LBB0_351
	s_or_b64 exec, exec, s[62:63]
	s_and_b64 vcc, exec, s[40:41]
	s_cbranch_vccnz .LBB0_352

; template <bool NEEDQ> __device__ __forceinline__ float chunk_front(const ChunkRegs& C, const ChunkRegs& N, bool stage_next, int cur, int dir, const bf16x8& bhi, const bf16x8& blo, float biasd, LAS unsigned char* lds, int tid) {
;     ...
;     float pre = 0.f, tot = 0.f;
; #pragma unroll
;     for (int g = 0; g < 8; ++g) { const float tv = TOT[g * 64 + d]; tot += tv; if (dir == 0 ? (g < grp) : (g > grp)) pre += tv; }
.LBB0_351:
	s_waitcnt lgkmcnt(0)
	v_add_f32_e32 v18, v18, v19
	s_or_b64 exec, exec, s[62:63]
	s_and_b64 vcc, exec, s[40:41]
	s_cbranch_vccz .LBB0_350

; template <bool NEEDQ> __device__ __forceinline__ float chunk_front(const ChunkRegs& C, const ChunkRegs& N, bool stage_next, int cur, int dir, const bf16x8& bhi, const bf16x8& blo, float biasd, LAS unsigned char* lds, int tid) {
;     ...
;     float pre = 0.f, tot = 0.f;
; #pragma unroll
;     for (int g = 0; g < 8; ++g) { const float tv = TOT[g * 64 + d]; tot += tv; if (dir == 0 ? (g < grp) : (g > grp)) pre += tv; }
.LBB0_357:
	s_waitcnt lgkmcnt(0)
	v_add_f32_e32 v18, v18, v20
	s_or_b64 exec, exec, s[62:63]
	s_and_b64 vcc, exec, s[40:41]
	s_cbranch_vccz .LBB0_356

; template <bool NEEDQ> __device__ __forceinline__ float chunk_front(const ChunkRegs& C, const ChunkRegs& N, bool stage_next, int cur, int dir, const bf16x8& bhi, const bf16x8& blo, float biasd, LAS unsigned char* lds, int tid) {
;     ...
;     float pre = 0.f, tot = 0.f;
; #pragma unroll
;     for (int g = 0; g < 8; ++g) { const float tv = TOT[g * 64 + d]; tot += tv; if (dir == 0 ? (g < grp) : (g > grp)) pre += tv; }
.LBB0_363:
	s_waitcnt lgkmcnt(0)
	v_add_f32_e32 v18, v18, v21
	s_or_b64 exec, exec, s[62:63]
	s_and_b64 vcc, exec, s[40:41]
	s_cbranch_vccz .LBB0_362

; template <bool NEEDQ> __device__ __forceinline__ float chunk_front(const ChunkRegs& C, const ChunkRegs& N, bool stage_next, int cur, int dir, const bf16x8& bhi, const bf16x8& blo, float biasd, LAS unsigned char* lds, int tid) {
;     ...
;     float pre = 0.f, tot = 0.f;
; #pragma unroll
;     for (int g = 0; g < 8; ++g) { const float tv = TOT[g * 64 + d]; tot += tv; if (dir == 0 ? (g < grp) : (g > grp)) pre += tv; }
.LBB0_369:
	s_waitcnt lgkmcnt(0)
	v_add_f32_e32 v18, v18, v22
	s_or_b64 exec, exec, s[62:63]
	s_and_b64 vcc, exec, s[40:41]
	s_cbranch_vccz .LBB0_368

; template <bool NEEDQ> __device__ __forceinline__ float chunk_front(const ChunkRegs& C, const ChunkRegs& N, bool stage_next, int cur, int dir, const bf16x8& bhi, const bf16x8& blo, float biasd, LAS unsigned char* lds, int tid) {
;     ...
;     float pre = 0.f, tot = 0.f;
; #pragma unroll
;     for (int g = 0; g < 8; ++g) { const float tv = TOT[g * 64 + d]; tot += tv; if (dir == 0 ? (g < grp) : (g > grp)) pre += tv; }
.LBB0_375:
	s_waitcnt lgkmcnt(0)
	v_add_f32_e32 v18, v18, v23
	s_or_b64 exec, exec, s[62:63]
	s_and_b64 vcc, exec, s[40:41]
	s_cbranch_vccz .LBB0_374

; template <bool NEEDQ> __device__ __forceinline__ float chunk_front(const ChunkRegs& C, const ChunkRegs& N, bool stage_next, int cur, int dir, const bf16x8& bhi, const bf16x8& blo, float biasd, LAS unsigned char* lds, int tid) {
;     ...
;     float pre = 0.f, tot = 0.f;
; #pragma unroll
;     for (int g = 0; g < 8; ++g) { const float tv = TOT[g * 64 + d]; tot += tv; if (dir == 0 ? (g < grp) : (g > grp)) pre += tv; }
.LBB0_381:
	s_waitcnt lgkmcnt(0)
	v_add_f32_e32 v18, v18, v31
	s_or_b64 exec, exec, s[62:63]
	s_and_b64 vcc, exec, s[40:41]
	s_cbranch_vccz .LBB0_380

; template <bool NEEDQ> __device__ __forceinline__ float chunk_front(const ChunkRegs& C, const ChunkRegs& N, bool stage_next, int cur, int dir, const bf16x8& bhi, const bf16x8& blo, float biasd, LAS unsigned char* lds, int tid) {
;     ...
;         TOT[grp * 64 + d] = la[7];
;     } else {
; #pragma unroll
;         for (int i = 6; i >= 0; --i) la[i] += la[i + 1];
;         TOT[grp * 64 + d] = la[0];
;     }
;     __syncthreads();
;     float pre = 0.f, tot = 0.f;
; #pragma unroll
;     for (int g = 0; g < 8; ++g) { const float tv = TOT[g * 64 + d]; tot += tv; if (dir == 0 ? (g < grp) : (g > grp)) pre += tv; }
.LBB0_530:
	ds_write_b32 v204, v79 offset:20480
	s_waitcnt lgkmcnt(0)
	s_barrier
	ds_read_b32 v64, v202 offset:20480
	ds_read_b32 v67, v202 offset:20736
	ds_read_b32 v68, v202 offset:20992
	ds_read_b32 v69, v202 offset:21248
	ds_read_b32 v70, v202 offset:21504
	ds_read_b32 v71, v202 offset:21760
	ds_read_b32 v79, v202 offset:22016
	ds_read_b32 v116, v202 offset:22272
	s_and_b64 vcc, exec, s[62:63]
	s_cbranch_vccz .LBB0_532
	v_readlane_b32 s48, v253, 24
	v_readlane_b32 s49, v253, 25
	s_and_b64 s[48:49], s[48:49], exec
	s_cbranch_execz .LBB0_533
	s_branch .LBB0_534

; template <bool NEEDQ> __device__ __forceinline__ float chunk_front(const ChunkRegs& C, const ChunkRegs& N, bool stage_next, int cur, int dir, const bf16x8& bhi, const bf16x8& blo, float biasd, LAS unsigned char* lds, int tid) {
;     ...
;     float pre = 0.f, tot = 0.f;
; #pragma unroll
;     for (int g = 0; g < 8; ++g) { const float tv = TOT[g * 64 + d]; tot += tv; if (dir == 0 ? (g < grp) : (g > grp)) pre += tv; }
.LBB0_534:
	s_waitcnt lgkmcnt(0)
	v_add_f32_e32 v64, 0, v64
	v_mov_b32_e32 v66, 0
	s_and_saveexec_b64 vcc, s[48:49]
	s_cbranch_execnz .LBB0_537
	s_or_b64 exec, exec, vcc
	s_and_b64 vcc, exec, s[44:45]
	s_cbranch_vccnz .LBB0_538

; template <bool NEEDQ> __device__ __forceinline__ float chunk_front(const ChunkRegs& C, const ChunkRegs& N, bool stage_next, int cur, int dir, const bf16x8& bhi, const bf16x8& blo, float biasd, LAS unsigned char* lds, int tid) {
;     ...
;     float pre = 0.f, tot = 0.f;
; #pragma unroll
;     for (int g = 0; g < 8; ++g) { const float tv = TOT[g * 64 + d]; tot += tv; if (dir == 0 ? (g < grp) : (g > grp)) pre += tv; }
.LBB0_537:
	v_mov_b32_e32 v66, v64
	s_or_b64 exec, exec, vcc
	s_and_b64 vcc, exec, s[44:45]
	s_cbranch_vccz .LBB0_536

; template <bool NEEDQ> __device__ __forceinline__ float chunk_front(const ChunkRegs& C, const ChunkRegs& N, bool stage_next, int cur, int dir, const bf16x8& bhi, const bf16x8& blo, float biasd, LAS unsigned char* lds, int tid) {
;     ...
;     float pre = 0.f, tot = 0.f;
; #pragma unroll
;     for (int g = 0; g < 8; ++g) { const float tv = TOT[g * 64 + d]; tot += tv; if (dir == 0 ? (g < grp) : (g > grp)) pre += tv; }
.LBB0_540:
	s_and_saveexec_b64 vcc, s[48:49]
	s_cbranch_execnz .LBB0_543
	s_or_b64 exec, exec, vcc
	s_and_b64 vcc, exec, s[44:45]
	s_cbranch_vccnz .LBB0_544

; template <bool NEEDQ> __device__ __forceinline__ float chunk_front(const ChunkRegs& C, const ChunkRegs& N, bool stage_next, int cur, int dir, const bf16x8& bhi, const bf16x8& blo, float biasd, LAS unsigned char* lds, int tid) {
;     ...
;     float pre = 0.f, tot = 0.f;
; #pragma unroll
;     for (int g = 0; g < 8; ++g) { const float tv = TOT[g * 64 + d]; tot += tv; if (dir == 0 ? (g < grp) : (g > grp)) pre += tv; }
.LBB0_543:
	s_waitcnt lgkmcnt(0)
	v_add_f32_e32 v66, v66, v67
	s_or_b64 exec, exec, vcc
	s_and_b64 vcc, exec, s[44:45]
	s_cbranch_vccz .LBB0_542

; template <bool NEEDQ> __device__ __forceinline__ float chunk_front(const ChunkRegs& C, const ChunkRegs& N, bool stage_next, int cur, int dir, const bf16x8& bhi, const bf16x8& blo, float biasd, LAS unsigned char* lds, int tid) {
;     ...
;     float pre = 0.f, tot = 0.f;
; #pragma unroll
;     for (int g = 0; g < 8; ++g) { const float tv = TOT[g * 64 + d]; tot += tv; if (dir == 0 ? (g < grp) : (g > grp)) pre += tv; }
.LBB0_549:
	s_waitcnt lgkmcnt(0)
	v_add_f32_e32 v66, v66, v68
	s_or_b64 exec, exec, vcc
	s_and_b64 vcc, exec, s[44:45]
	s_cbranch_vccz .LBB0_548

; template <bool NEEDQ> __device__ __forceinline__ float chunk_front(const ChunkRegs& C, const ChunkRegs& N, bool stage_next, int cur, int dir, const bf16x8& bhi, const bf16x8& blo, float biasd, LAS unsigned char* lds, int tid) {
;     ...
;     float pre = 0.f, tot = 0.f;
; #pragma unroll
;     for (int g = 0; g < 8; ++g) { const float tv = TOT[g * 64 + d]; tot += tv; if (dir == 0 ? (g < grp) : (g > grp)) pre += tv; }
.LBB0_555:
	s_waitcnt lgkmcnt(0)
	v_add_f32_e32 v66, v66, v69
	s_or_b64 exec, exec, vcc
	s_and_b64 vcc, exec, s[44:45]
	s_cbranch_vccz .LBB0_554

; template <bool NEEDQ> __device__ __forceinline__ float chunk_front(const ChunkRegs& C, const ChunkRegs& N, bool stage_next, int cur, int dir, const bf16x8& bhi, const bf16x8& blo, float biasd, LAS unsigned char* lds, int tid) {
;     ...
;     float pre = 0.f, tot = 0.f;
; #pragma unroll
;     for (int g = 0; g < 8; ++g) { const float tv = TOT[g * 64 + d]; tot += tv; if (dir == 0 ? (g < grp) : (g > grp)) pre += tv; }
.LBB0_561:
	s_waitcnt lgkmcnt(0)
	v_add_f32_e32 v66, v66, v70
	s_or_b64 exec, exec, vcc
	s_and_b64 vcc, exec, s[44:45]
	s_cbranch_vccz .LBB0_560

; template <bool NEEDQ> __device__ __forceinline__ float chunk_front(const ChunkRegs& C, const ChunkRegs& N, bool stage_next, int cur, int dir, const bf16x8& bhi, const bf16x8& blo, float biasd, LAS unsigned char* lds, int tid) {
;     ...
;     float pre = 0.f, tot = 0.f;
; #pragma unroll
;     for (int g = 0; g < 8; ++g) { const float tv = TOT[g * 64 + d]; tot += tv; if (dir == 0 ? (g < grp) : (g > grp)) pre += tv; }
.LBB0_567:
	s_waitcnt lgkmcnt(0)
	v_add_f32_e32 v66, v66, v71
	s_or_b64 exec, exec, vcc
	s_and_b64 vcc, exec, s[44:45]
	s_cbranch_vccz .LBB0_566

; template <bool NEEDQ> __device__ __forceinline__ float chunk_front(const ChunkRegs& C, const ChunkRegs& N, bool stage_next, int cur, int dir, const bf16x8& bhi, const bf16x8& blo, float biasd, LAS unsigned char* lds, int tid) {
;     ...
;     float pre = 0.f, tot = 0.f;
; #pragma unroll
;     for (int g = 0; g < 8; ++g) { const float tv = TOT[g * 64 + d]; tot += tv; if (dir == 0 ? (g < grp) : (g > grp)) pre += tv; }
.LBB0_573:
	s_waitcnt lgkmcnt(0)
	v_add_f32_e32 v66, v66, v79
	s_or_b64 exec, exec, vcc
	s_and_b64 vcc, exec, s[44:45]
	s_cbranch_vccz .LBB0_572

; __device__ __forceinline__ void attn_unit(const bf16* Hb, const bf16* KD, const bf16* VD, bf16* MIX, int row0, int S, int head, int qb, float lam, const float* dng, float kn0, float kn1, LAS unsigned char* lds, int wave_u) {
;     ...
;     for (int t = tlo; t <= thi; t += 2) {
;         const int pbuf = ((t - tlo) >> 1) & 1;
;         if (t + 2 <= thi) { ATT_DMA(t + 2, 2 * (pbuf ^ 1)); ATT_DMA(t + 3, 2 * (pbuf ^ 1) + 1); }
.LBB0_657:
	s_and_b32 s44, s57, 1
	s_add_i32 s73, s73, 2
	s_cmp_gt_i32 s73, s74
	s_cselect_b64 s[0:1], -1, 0
	s_lshl_b32 s59, s44, 16
